# scan loader: per-call elementwise core hand-written (packed f32 math, divisions without inactive div_scale steps, same op order); dead mu_v address math removed
# speedup vs baseline: 1.0164x; 1.0164x over previous
; #define KP(f) ((decltype(Params::f))karg_ptr<(int)offsetof(Params, f)>())
; __device__ void phase_scan(int l, unsigned char* lds) {
;     int tid_ = threadIdx.x; asm volatile("" : "+v"(tid_));
;     const int tid = tid_, wid = tid >> 6, lane = tid & 63, G = gridDim.x;
;     const bool loader = wid >= 4;
;     if (!loader) __builtin_amdgcn_s_setprio(3);
;     ScanPtrs Q;
;     Q.z = KP(z); Q.sw = KP(xb) + (size_t)T_ALL * 512; Q.sa = KP(sc_a); Q.st_shift = KP(state_shift) + (size_t)l * NSB * DSH; Q.mu = KP(mu_shift) + (size_t)l * DSH;
;     Q.k_k = KP(k_k) + (size_t)l * 512; Q.k_a = KP(k_a) + (size_t)l * 512; Q.r_k = KP(r_k) + (size_t)l * 512; Q.decay0 = KP(decay0) + (size_t)l * 512; Q.a0 = KP(a0) + (size_t)l * 512; Q.rk = KP(rk);
;     bf16_t* ybuf = KP(xb);
;     const float* st_wkv = KP(state_wkv); float* out = KP(out);
;     int J = (G % 8 == 0) ? (int)(blockIdx.x % 8) * (G / 8) + (int)(blockIdx.x / 8) : (int)blockIdx.x, ci = 0, it = 0;
;     int Ji = J, cis = 0;
;     int Jg = J, cg_ = 0;
;     LStage L, L2;
;     f32x2 s01 = (f32x2){0.f, 0.f}, s23 = s01;
;     f32x4 s_pref = (f32x4){0.f, 0.f, 0.f, 0.f};
;     if (!loader && J >= 256 && J < NJOBS) { const Job j0 = job_decode(J, 0); s_pref = *(const f32x4*)(st_wkv + (((((size_t)l * NSB + j0.seq) * 8 + j0.h) * 64 + j0.rs * 16 + (wid * 4 + (lane >> 4))) * 64 + (lane & 15) * 4)); }
.LBB0_401:
	s_or_b64 exec, exec, s[8:9]
	s_mov_b32 s6, s46
	s_mov_b32 s7, s2
	v_mov_b32_e32 v53, v166
	s_waitcnt lgkmcnt(0)
	s_barrier
	s_nop 0
	v_ashrrev_i32_e32 v52, 6, v53
	s_mov_b32 s98, -1
	v_mov_b32_e32 v252, 0xbfb8aa3b
	v_mov_b32_e32 v254, 0xbf1b4598
	v_mov_b32_e32 v226, 0x3fb8aa3b
	v_cmp_lt_i32_e64 s[10:11], 3, v52
	v_cmp_gt_i32_e64 s[12:13], 4, v52
	s_and_saveexec_b64 s[8:9], s[12:13]
	s_setprio 3
	s_or_b64 exec, exec, s[8:9]
	s_load_dwordx2 s[24:25], s[0:1], 0x130
	s_waitcnt lgkmcnt(0)
	s_load_dwordx2 s[14:15], s[0:1], 0x120
	s_waitcnt lgkmcnt(0)
	s_load_dwordx2 s[26:27], s[0:1], 0x140
	s_waitcnt lgkmcnt(0)
	s_load_dwordx2 s[28:29], s[0:1], 16
	s_waitcnt lgkmcnt(0)
	s_load_dwordx2 s[30:31], s[0:1], 56
	s_waitcnt lgkmcnt(0)
	s_load_dwordx2 s[34:35], s[0:1], 0x68
	s_waitcnt lgkmcnt(0)
	s_load_dwordx2 s[36:37], s[0:1], 0x70
	s_waitcnt lgkmcnt(0)
	s_load_dwordx2 s[38:39], s[0:1], 0x78
	s_waitcnt lgkmcnt(0)
	s_load_dwordx2 s[40:41], s[0:1], 64
	s_waitcnt lgkmcnt(0)
	s_load_dwordx2 s[56:57], s[0:1], 0x50
	s_waitcnt lgkmcnt(0)
	s_load_dwordx2 s[58:59], s[0:1], 0x150
	s_waitcnt lgkmcnt(0)
	s_load_dwordx2 s[60:61], s[0:1], 0x120
	s_waitcnt lgkmcnt(0)
	s_load_dwordx2 s[22:23], s[0:1], 32
	s_waitcnt lgkmcnt(0)
	s_load_dwordx2 s[62:63], s[0:1], 0xd8
	s_waitcnt lgkmcnt(0)
	v_cndmask_b32_e64 v0, 0, 1, s[54:55]
	v_cmp_ne_u32_e64 s[6:7], 1, v0
	s_andn2_b64 vcc, exec, s[54:55]
	s_mov_b32 s51, s2
	v_writelane_b32 v230, s6, 6
	s_nop 1
	v_writelane_b32 v230, s7, 7
	s_cbranch_vccnz .LBB0_405
	s_and_b32 s6, s2, 7
	s_ashr_i32 s7, s46, 3
	s_mul_i32 s6, s7, s6
	s_lshr_b32 s7, s2, 3
	s_add_i32 s51, s6, s7

; __device__ __forceinline__ float sigmoidf_(float x) { return 1.0f / (1.0f + __expf(-x)); }
; __device__ __forceinline__ f32x4 cv_bf4(const u32x2 w) { return (f32x4){bflo(w.x), bfhi(w.x), bflo(w.y), bfhi(w.y)}; }
; __device__ __forceinline__ void scan_finish(const ScanPtrs& Q, int J, int ci, unsigned char* buf, int ltid, const LStage& L, int toff) {
;     const Job jb = job_decode(J, ci);
;     const int tt = (ltid >> 4) + toff, c = (ltid & 15) * 4;
;     if (tt < jb.nsteps) {
;         const int tok = jb.tok0 + tt; const int tseq = jb.is_s ? tt : ci * SC_CH + tt;
;         const int gc = jb.h * 64 + c;
;         f32x4 r = cv_bf4(L.r), k0 = cv_bf4(L.k), v = cv_bf4(L.v), rp, kp, vp;
;         if (tseq > 0) { rp = cv_bf4(L.rp); kp = cv_bf4(L.kp); vp = cv_bf4(L.vp); }
;         else if (jb.is_s) { rp = L.fr; kp = L.fk; vp = L.fv; }
;         else { rp = (f32x4){0.f, 0.f, 0.f, 0.f}; kp = rp; vp = rp; }
;         const float* mu = Q.mu + gc;
;         r = r + (rp - r) * *(const f32x4*)mu; k0 = k0 + (kp - k0) * *(const f32x4*)(mu + 512); v = v + (vp - v) * *(const f32x4*)(mu + 1024);
;         const f32x4 kk = k0 * *(const f32x4*)(Q.k_k + gc);
;         const float ss = allsum16((kk[0] * kk[0] + kk[1] * kk[1]) + (kk[2] * kk[2] + kk[3] * kk[3]));
;         const float inv = 1.0f / fmaxf(sqrtf(ss), 1e-12f);
;         const f32x4 kkn = kk * inv;
;         const f32x4 dw = cv_bf4(L.sw) + *(const f32x4*)(Q.decay0 + gc);
;         const f32x4 da = cv_bf4(L.sa) + *(const f32x4*)(Q.a0 + gc);
;         f32x4 dec, ain;
; #pragma unroll
;         for (int j = 0; j < 4; ++j) { dec[j] = __expf(-0.60653066f * sigmoidf_(dw[j])); ain[j] = sigmoidf_(da[j]); }
;         const f32x4 ka = *(const f32x4*)(Q.k_a + gc);
;         const f32x4 kf = k0 * (1.0f + (ain - 1.0f) * ka);
;         const f32x4 rkw = *(const f32x4*)(Q.r_k + gc);
;         const f32x4 pr = r * kf * rkw;
;         const float rk = allsum16((pr[0] + pr[1]) + (pr[2] + pr[3]));
.Lprm_ok_0:
	s_waitcnt vmcnt(0)
	v_lshlrev_b32_e32 v232, 16, v70
	v_and_b32_e32 v233, 0xffff0000, v70
	v_lshlrev_b32_e32 v234, 16, v71
	v_and_b32_e32 v235, 0xffff0000, v71
	v_pk_add_f32 v[236:237], v[50:51], v[232:233] neg_lo:[0,1] neg_hi:[0,1]
	v_pk_add_f32 v[238:239], v[52:53], v[234:235] neg_lo:[0,1] neg_hi:[0,1]
	v_pk_fma_f32 v[232:233], v[236:237], v[186:187], v[232:233]
	v_pk_fma_f32 v[234:235], v[238:239], v[188:189], v[234:235]
	v_pk_mul_f32 v[236:237], v[232:233], v[198:199]
	v_pk_mul_f32 v[238:239], v[234:235], v[200:201]
	v_pk_mul_f32 v[240:241], v[236:237], v[236:237]
	v_pk_mul_f32 v[242:243], v[238:239], v[238:239]
	v_add_f32_e32 v240, v240, v241
	v_add_f32_e32 v242, v242, v243
	v_lshlrev_b32_e32 v244, 16, v82
	v_and_b32_e32 v245, 0xffff0000, v82
	v_lshlrev_b32_e32 v246, 16, v83
	v_and_b32_e32 v247, 0xffff0000, v83
	v_add_f32_e32 v240, v240, v242
	v_lshlrev_b32_e32 v248, 16, v84
	v_and_b32_e32 v249, 0xffff0000, v84
	v_lshlrev_b32_e32 v250, 16, v85
	v_and_b32_e32 v251, 0xffff0000, v85
	v_add_f32_dpp v240, v240, v240 quad_perm:[1,0,3,2] row_mask:0xf bank_mask:0xf bound_ctrl:1
	v_pk_add_f32 v[244:245], v[244:245], v[190:191]
	v_pk_add_f32 v[246:247], v[246:247], v[192:193]
	v_add_f32_dpp v240, v240, v240 quad_perm:[2,3,0,1] row_mask:0xf bank_mask:0xf bound_ctrl:1
	v_pk_add_f32 v[248:249], v[248:249], v[194:195]
	v_pk_add_f32 v[250:251], v[250:251], v[196:197]
	v_add_f32_dpp v240, v240, v240 row_half_mirror row_mask:0xf bank_mask:0xf bound_ctrl:1
	v_pk_mul_f32 v[244:245], v[244:245], v[252:253] op_sel_hi:[1,0]
	v_pk_mul_f32 v[246:247], v[246:247], v[252:253] op_sel_hi:[1,0]
	v_add_f32_dpp v240, v240, v240 row_mirror row_mask:0xf bank_mask:0xf bound_ctrl:1
	v_pk_mul_f32 v[248:249], v[248:249], v[252:253] op_sel_hi:[1,0]
	v_pk_mul_f32 v[250:251], v[250:251], v[252:253] op_sel_hi:[1,0]
	v_exp_f32_e32 v244, v244
	v_exp_f32_e32 v245, v245
	v_exp_f32_e32 v246, v246
	v_exp_f32_e32 v247, v247
	v_mul_f32_e32 v241, 0x4f800000, v240
	v_cmp_gt_f32_e32 vcc, s78, v240
	v_exp_f32_e32 v248, v248
	v_exp_f32_e32 v249, v249
	v_cndmask_b32_e32 v240, v240, v241, vcc
	v_sqrt_f32_e32 v241, v240
	v_exp_f32_e32 v250, v250
	v_exp_f32_e32 v251, v251
	v_pk_add_f32 v[244:245], v[244:245], 1.0 op_sel_hi:[1,0]
	v_pk_add_f32 v[246:247], v[246:247], 1.0 op_sel_hi:[1,0]
	v_add_u32_e32 v242, -1, v241
	v_add_u32_e32 v243, 1, v241
	v_fma_f32 v253, -v242, v241, v240
	v_fma_f32 v255, -v243, v241, v240
	v_cmp_ge_f32_e64 s[22:23], 0, v253
	v_pk_add_f32 v[248:249], v[248:249], 1.0 op_sel_hi:[1,0]
	v_pk_add_f32 v[250:251], v[250:251], 1.0 op_sel_hi:[1,0]
	v_cndmask_b32_e64 v241, v241, v242, s[22:23]
	v_cmp_lt_f32_e64 s[22:23], 0, v255
	v_rcp_f32_e32 v218, v244
	v_rcp_f32_e32 v219, v245
	v_cndmask_b32_e64 v241, v241, v243, s[22:23]
	v_rcp_f32_e32 v220, v246
	v_mul_f32_e32 v242, 0x37800000, v241
	v_rcp_f32_e32 v221, v247
	v_cndmask_b32_e32 v241, v241, v242, vcc
	v_cmp_class_f32_e32 vcc, v240, v118
	v_rcp_f32_e32 v222, v248
	v_rcp_f32_e32 v223, v249
	v_cndmask_b32_e32 v240, v241, v240, vcc
	v_rcp_f32_e32 v224, v250
	v_max_f32_e32 v240, 0x2b8cbccc, v240
	v_rcp_f32_e32 v225, v251
	v_pk_fma_f32 v[136:137], v[244:245], v[218:219], 1.0 op_sel_hi:[1,1,0] neg_lo:[1,0,0] neg_hi:[1,0,0]
	v_pk_fma_f32 v[138:139], v[246:247], v[220:221], 1.0 op_sel_hi:[1,1,0] neg_lo:[1,0,0] neg_hi:[1,0,0]
	v_pk_fma_f32 v[218:219], v[136:137], v[218:219], v[218:219]
	v_pk_fma_f32 v[220:221], v[138:139], v[220:221], v[220:221]
	v_pk_fma_f32 v[136:137], v[244:245], v[218:219], 1.0 op_sel_hi:[1,1,0] neg_lo:[1,0,0] neg_hi:[1,0,0]
	v_pk_fma_f32 v[138:139], v[246:247], v[220:221], 1.0 op_sel_hi:[1,1,0] neg_lo:[1,0,0] neg_hi:[1,0,0]
	v_pk_fma_f32 v[140:141], v[136:137], v[218:219], v[218:219]
	v_pk_fma_f32 v[142:143], v[138:139], v[220:221], v[220:221]
	v_pk_fma_f32 v[136:137], v[244:245], v[140:141], 1.0 op_sel_hi:[1,1,0] neg_lo:[1,0,0] neg_hi:[1,0,0]
	v_pk_fma_f32 v[138:139], v[246:247], v[142:143], 1.0 op_sel_hi:[1,1,0] neg_lo:[1,0,0] neg_hi:[1,0,0]
	v_pk_fma_f32 v[140:141], v[136:137], v[218:219], v[140:141]
	v_pk_fma_f32 v[142:143], v[138:139], v[220:221], v[142:143]
	v_rcp_f32_e32 v241, v240
	v_div_fixup_f32 v244, v140, v244, 1.0
	v_div_fixup_f32 v245, v141, v245, 1.0
	v_div_fixup_f32 v246, v142, v246, 1.0
	v_div_fixup_f32 v247, v143, v247, 1.0
; __device__ __forceinline__ float sigmoidf_(float x) { return 1.0f / (1.0f + __expf(-x)); }
; __device__ __forceinline__ f32x4 cv_bf4(const u32x2 w) { return (f32x4){bflo(w.x), bfhi(w.x), bflo(w.y), bfhi(w.y)}; }
; __device__ __forceinline__ void scan_finish(const ScanPtrs& Q, int J, int ci, unsigned char* buf, int ltid, const LStage& L, int toff) {
;     ...
;         r = r + (rp - r) * *(const f32x4*)mu; k0 = k0 + (kp - k0) * *(const f32x4*)(mu + 512); v = v + (vp - v) * *(const f32x4*)(mu + 1024);
;         const f32x4 kk = k0 * *(const f32x4*)(Q.k_k + gc);
;         const float ss = allsum16((kk[0] * kk[0] + kk[1] * kk[1]) + (kk[2] * kk[2] + kk[3] * kk[3]));
;         const float inv = 1.0f / fmaxf(sqrtf(ss), 1e-12f);
;         const f32x4 kkn = kk * inv;
;         const f32x4 dw = cv_bf4(L.sw) + *(const f32x4*)(Q.decay0 + gc);
;         const f32x4 da = cv_bf4(L.sa) + *(const f32x4*)(Q.a0 + gc);
;         f32x4 dec, ain;
; #pragma unroll
;         for (int j = 0; j < 4; ++j) { dec[j] = __expf(-0.60653066f * sigmoidf_(dw[j])); ain[j] = sigmoidf_(da[j]); }
;         const f32x4 ka = *(const f32x4*)(Q.k_a + gc);
;         const f32x4 kf = k0 * (1.0f + (ain - 1.0f) * ka);
;         const f32x4 rkw = *(const f32x4*)(Q.r_k + gc);
;         const f32x4 pr = r * kf * rkw;
;         const float rk = allsum16((pr[0] + pr[1]) + (pr[2] + pr[3]));
;         unsigned char* tb = buf + tt * SC_TOKB + c * 4;
;         *(f32x4*)(tb) = -kkn; *(f32x4*)(tb + 256) = dec; *(f32x4*)(tb + 512) = kkn * ain; *(f32x4*)(tb + 768) = kf; *(f32x4*)(tb + 1024) = r;
;         if ((c >> 4) == jb.rs) *(f32x4*)(buf + tt * SC_TOKB + 1280 + (c & 15) * 4) = v;
;         if (jb.rs == 0 && c == 0) Q.rk[(size_t)tok * 8 + jb.h] = rk;
	v_fma_f32 v242, -v240, v241, 1.0
	v_fmac_f32_e32 v241, v242, v241
	v_mul_f32_e32 v242, -1.0, v241
	v_fma_f32 v243, -v240, v242, -1.0
	v_fmac_f32_e32 v242, v243, v241
	v_fma_f32 v243, -v240, v242, -1.0
	v_fma_f32 v242, v243, v241, v242
	v_div_fixup_f32 v242, v242, v240, -1.0
	v_pk_mul_f32 v[244:245], v[244:245], v[254:255] op_sel_hi:[1,0]
	v_pk_mul_f32 v[246:247], v[246:247], v[254:255] op_sel_hi:[1,0]
	v_pk_mul_f32 v[244:245], v[244:245], v[226:227] op_sel_hi:[1,0]
	v_pk_mul_f32 v[246:247], v[246:247], v[226:227] op_sel_hi:[1,0]
	v_pk_fma_f32 v[136:137], v[248:249], v[222:223], 1.0 op_sel_hi:[1,1,0] neg_lo:[1,0,0] neg_hi:[1,0,0]
	v_pk_fma_f32 v[138:139], v[250:251], v[224:225], 1.0 op_sel_hi:[1,1,0] neg_lo:[1,0,0] neg_hi:[1,0,0]
	v_pk_fma_f32 v[222:223], v[136:137], v[222:223], v[222:223]
	v_pk_fma_f32 v[224:225], v[138:139], v[224:225], v[224:225]
	v_pk_fma_f32 v[136:137], v[248:249], v[222:223], 1.0 op_sel_hi:[1,1,0] neg_lo:[1,0,0] neg_hi:[1,0,0]
	v_pk_fma_f32 v[138:139], v[250:251], v[224:225], 1.0 op_sel_hi:[1,1,0] neg_lo:[1,0,0] neg_hi:[1,0,0]
	v_pk_fma_f32 v[140:141], v[136:137], v[222:223], v[222:223]
	v_pk_fma_f32 v[142:143], v[138:139], v[224:225], v[224:225]
	v_pk_fma_f32 v[136:137], v[248:249], v[140:141], 1.0 op_sel_hi:[1,1,0] neg_lo:[1,0,0] neg_hi:[1,0,0]
	v_pk_fma_f32 v[138:139], v[250:251], v[142:143], 1.0 op_sel_hi:[1,1,0] neg_lo:[1,0,0] neg_hi:[1,0,0]
	v_pk_fma_f32 v[140:141], v[136:137], v[222:223], v[140:141]
	v_pk_fma_f32 v[142:143], v[138:139], v[224:225], v[142:143]
	v_exp_f32_e32 v244, v244
	v_exp_f32_e32 v245, v245
	v_exp_f32_e32 v246, v246
	v_exp_f32_e32 v247, v247
	v_div_fixup_f32 v248, v140, v248, 1.0
	v_div_fixup_f32 v249, v141, v249, 1.0
	v_div_fixup_f32 v250, v142, v250, 1.0
	v_div_fixup_f32 v251, v143, v251, 1.0
	v_pk_mul_f32 v[218:219], v[236:237], v[242:243] op_sel_hi:[1,0]
	v_pk_mul_f32 v[220:221], v[238:239], v[242:243] op_sel_hi:[1,0]
	v_pk_add_f32 v[136:137], v[248:249], -1.0 op_sel_hi:[1,0]
	v_pk_add_f32 v[138:139], v[250:251], -1.0 op_sel_hi:[1,0]
	v_pk_mul_f32 v[222:223], v[218:219], v[248:249] neg_lo:[1,0] neg_hi:[1,0]
	v_pk_mul_f32 v[224:225], v[220:221], v[250:251] neg_lo:[1,0] neg_hi:[1,0]
	v_pk_fma_f32 v[136:137], v[206:207], v[136:137], 1.0 op_sel_hi:[1,1,0]
	v_pk_fma_f32 v[138:139], v[208:209], v[138:139], 1.0 op_sel_hi:[1,1,0]
	v_lshlrev_b32_e32 v140, 16, v62
	v_and_b32_e32 v141, 0xffff0000, v62
	v_lshlrev_b32_e32 v142, 16, v63
	v_and_b32_e32 v143, 0xffff0000, v63
	v_pk_mul_f32 v[136:137], v[232:233], v[136:137]
	v_pk_mul_f32 v[138:139], v[234:235], v[138:139]
	v_pk_add_f32 v[146:147], v[46:47], v[140:141] neg_lo:[0,1] neg_hi:[0,1]
	v_pk_add_f32 v[148:149], v[48:49], v[142:143] neg_lo:[0,1] neg_hi:[0,1]
	v_pk_fma_f32 v[140:141], v[146:147], v[202:203], v[140:141]
	v_pk_fma_f32 v[142:143], v[148:149], v[204:205], v[142:143]
	v_pk_mul_f32 v[146:147], v[140:141], v[136:137]
	v_pk_mul_f32 v[148:149], v[142:143], v[138:139]
	v_pk_mul_f32 v[146:147], v[210:211], v[146:147]
	v_pk_mul_f32 v[148:149], v[212:213], v[148:149]
	v_add_u32_e32 v30, s6, v99
	v_add_f32_e32 v20, v146, v147
	v_add_f32_e32 v21, v148, v149
	v_add_u32_e32 v31, v30, v100
	v_add_f32_e32 v20, v20, v21
	v_mov_b32_e32 v21, 0
	ds_write_b128 v31, v[218:221]
	v_add_f32_dpp v20, v20, v20 quad_perm:[1,0,3,2] row_mask:0xf bank_mask:0xf bound_ctrl:1
	ds_write_b128 v31, v[244:247] offset:256
	ds_write_b128 v31, v[222:225] offset:512
	v_add_f32_dpp v20, v20, v20 quad_perm:[2,3,0,1] row_mask:0xf bank_mask:0xf bound_ctrl:1
	ds_write_b128 v31, v[136:139] offset:768
	ds_write_b128 v31, v[140:143] offset:1024
	v_add_f32_dpp v20, v20, v20 row_half_mirror row_mask:0xf bank_mask:0xf bound_ctrl:1
	v_cmp_eq_u32_e32 vcc, v101, v121
	s_nop 0
	v_mov_b32_dpp v21, v20 row_mirror row_mask:0xf bank_mask:0xf
	s_and_saveexec_b64 s[18:19], vcc
	s_cbranch_execz .LBB0_490
	v_lshlrev_b32_e32 v36, 16, v72
	v_and_b32_e32 v37, 0xffff0000, v72
	v_lshlrev_b32_e32 v38, 16, v73
	v_and_b32_e32 v39, 0xffff0000, v73
	v_sub_f32_e32 v29, v29, v39
	v_sub_f32_e32 v28, v28, v38
	v_sub_f32_e32 v27, v27, v37
	v_sub_f32_e32 v26, v26, v36
	v_add_u32_e32 v18, v30, v102
	s_waitcnt vmcnt(0)
	v_pk_fma_f32 v[26:27], v[26:27], v[214:215], v[36:37]
	v_pk_fma_f32 v[28:29], v[28:29], v[216:217], v[38:39]
	ds_write_b128 v18, v[26:29] offset:1280

; __device__ __forceinline__ float sigmoidf_(float x) { return 1.0f / (1.0f + __expf(-x)); }
; __device__ __forceinline__ f32x4 cv_bf4(const u32x2 w) { return (f32x4){bflo(w.x), bfhi(w.x), bflo(w.y), bfhi(w.y)}; }
; __device__ __forceinline__ void scan_finish(const ScanPtrs& Q, int J, int ci, unsigned char* buf, int ltid, const LStage& L, int toff) {
;     const Job jb = job_decode(J, ci);
;     const int tt = (ltid >> 4) + toff, c = (ltid & 15) * 4;
;     if (tt < jb.nsteps) {
;         const int tok = jb.tok0 + tt; const int tseq = jb.is_s ? tt : ci * SC_CH + tt;
;         const int gc = jb.h * 64 + c;
;         f32x4 r = cv_bf4(L.r), k0 = cv_bf4(L.k), v = cv_bf4(L.v), rp, kp, vp;
;         if (tseq > 0) { rp = cv_bf4(L.rp); kp = cv_bf4(L.kp); vp = cv_bf4(L.vp); }
;         else if (jb.is_s) { rp = L.fr; kp = L.fk; vp = L.fv; }
;         else { rp = (f32x4){0.f, 0.f, 0.f, 0.f}; kp = rp; vp = rp; }
;         const float* mu = Q.mu + gc;
;         r = r + (rp - r) * *(const f32x4*)mu; k0 = k0 + (kp - k0) * *(const f32x4*)(mu + 512); v = v + (vp - v) * *(const f32x4*)(mu + 1024);
;         const f32x4 kk = k0 * *(const f32x4*)(Q.k_k + gc);
;         const float ss = allsum16((kk[0] * kk[0] + kk[1] * kk[1]) + (kk[2] * kk[2] + kk[3] * kk[3]));
;         const float inv = 1.0f / fmaxf(sqrtf(ss), 1e-12f);
;         const f32x4 kkn = kk * inv;
;         const f32x4 dw = cv_bf4(L.sw) + *(const f32x4*)(Q.decay0 + gc);
;         const f32x4 da = cv_bf4(L.sa) + *(const f32x4*)(Q.a0 + gc);
;         f32x4 dec, ain;
; #pragma unroll
;         for (int j = 0; j < 4; ++j) { dec[j] = __expf(-0.60653066f * sigmoidf_(dw[j])); ain[j] = sigmoidf_(da[j]); }
;         const f32x4 ka = *(const f32x4*)(Q.k_a + gc);
;         const f32x4 kf = k0 * (1.0f + (ain - 1.0f) * ka);
;         const f32x4 rkw = *(const f32x4*)(Q.r_k + gc);
;         const f32x4 pr = r * kf * rkw;
;         const float rk = allsum16((pr[0] + pr[1]) + (pr[2] + pr[3]));
.LBB0_495:
	s_or_b64 exec, exec, s[16:17]
	v_lshl_or_b32 v18, v91, 8, v100
	s_waitcnt vmcnt(1)
	v_lshlrev_b32_e32 v232, 16, v60
	v_and_b32_e32 v233, 0xffff0000, v60
	v_lshlrev_b32_e32 v234, 16, v61
	v_and_b32_e32 v235, 0xffff0000, v61
	v_sub_f32_e32 v236, v52, v232
	v_sub_f32_e32 v237, v92, v233
	v_sub_f32_e32 v238, v53, v234
	v_sub_f32_e32 v239, v93, v235
	v_pk_fma_f32 v[232:233], v[236:237], v[186:187], v[232:233]
	v_pk_fma_f32 v[234:235], v[238:239], v[188:189], v[234:235]
	v_pk_mul_f32 v[236:237], v[232:233], v[198:199]
	v_pk_mul_f32 v[238:239], v[234:235], v[200:201]
	v_pk_mul_f32 v[240:241], v[236:237], v[236:237]
	v_pk_mul_f32 v[242:243], v[238:239], v[238:239]
	v_add_f32_e32 v240, v240, v241
	v_add_f32_e32 v242, v242, v243
	v_lshlrev_b32_e32 v244, 16, v78
	v_and_b32_e32 v245, 0xffff0000, v78
	v_lshlrev_b32_e32 v246, 16, v79
	v_and_b32_e32 v247, 0xffff0000, v79
	v_add_f32_e32 v240, v240, v242
	v_lshlrev_b32_e32 v248, 16, v80
	v_and_b32_e32 v249, 0xffff0000, v80
	v_lshlrev_b32_e32 v250, 16, v81
	v_and_b32_e32 v251, 0xffff0000, v81
	v_add_f32_dpp v240, v240, v240 quad_perm:[1,0,3,2] row_mask:0xf bank_mask:0xf bound_ctrl:1
	v_pk_add_f32 v[244:245], v[244:245], v[190:191]
	v_pk_add_f32 v[246:247], v[246:247], v[192:193]
	v_add_f32_dpp v240, v240, v240 quad_perm:[2,3,0,1] row_mask:0xf bank_mask:0xf bound_ctrl:1
	v_pk_add_f32 v[248:249], v[248:249], v[194:195]
	v_pk_add_f32 v[250:251], v[250:251], v[196:197]
	v_add_f32_dpp v240, v240, v240 row_half_mirror row_mask:0xf bank_mask:0xf bound_ctrl:1
	v_pk_mul_f32 v[244:245], v[244:245], v[252:253] op_sel_hi:[1,0]
	v_pk_mul_f32 v[246:247], v[246:247], v[252:253] op_sel_hi:[1,0]
	v_add_f32_dpp v240, v240, v240 row_mirror row_mask:0xf bank_mask:0xf bound_ctrl:1
	v_pk_mul_f32 v[248:249], v[248:249], v[252:253] op_sel_hi:[1,0]
	v_pk_mul_f32 v[250:251], v[250:251], v[252:253] op_sel_hi:[1,0]
	v_exp_f32_e32 v244, v244
	v_exp_f32_e32 v245, v245
	v_exp_f32_e32 v246, v246
	v_exp_f32_e32 v247, v247
	v_mul_f32_e32 v241, 0x4f800000, v240
	v_cmp_gt_f32_e32 vcc, s78, v240
	v_exp_f32_e32 v248, v248
	v_exp_f32_e32 v249, v249
	v_cndmask_b32_e32 v240, v240, v241, vcc
	v_sqrt_f32_e32 v241, v240
	v_exp_f32_e32 v250, v250
	v_exp_f32_e32 v251, v251
	v_pk_add_f32 v[244:245], v[244:245], 1.0 op_sel_hi:[1,0]
	v_pk_add_f32 v[246:247], v[246:247], 1.0 op_sel_hi:[1,0]
	v_add_u32_e32 v242, -1, v241
	v_add_u32_e32 v243, 1, v241
	v_fma_f32 v253, -v242, v241, v240
	v_fma_f32 v255, -v243, v241, v240
	v_cmp_ge_f32_e64 s[20:21], 0, v253
	v_pk_add_f32 v[248:249], v[248:249], 1.0 op_sel_hi:[1,0]
	v_pk_add_f32 v[250:251], v[250:251], 1.0 op_sel_hi:[1,0]
	v_cndmask_b32_e64 v241, v241, v242, s[20:21]
	v_cmp_lt_f32_e64 s[20:21], 0, v255
	v_rcp_f32_e32 v218, v244
	v_rcp_f32_e32 v219, v245
	v_cndmask_b32_e64 v241, v241, v243, s[20:21]
	v_rcp_f32_e32 v220, v246
	v_mul_f32_e32 v242, 0x37800000, v241
	v_rcp_f32_e32 v221, v247
	v_cndmask_b32_e32 v241, v241, v242, vcc
	v_cmp_class_f32_e32 vcc, v240, v118
	v_rcp_f32_e32 v222, v248
	v_rcp_f32_e32 v223, v249
	v_cndmask_b32_e32 v240, v241, v240, vcc
	v_rcp_f32_e32 v224, v250
	v_max_f32_e32 v240, 0x2b8cbccc, v240
	v_rcp_f32_e32 v225, v251
	v_pk_fma_f32 v[136:137], v[244:245], v[218:219], 1.0 op_sel_hi:[1,1,0] neg_lo:[1,0,0] neg_hi:[1,0,0]
	v_pk_fma_f32 v[138:139], v[246:247], v[220:221], 1.0 op_sel_hi:[1,1,0] neg_lo:[1,0,0] neg_hi:[1,0,0]
	v_pk_fma_f32 v[218:219], v[136:137], v[218:219], v[218:219]
	v_pk_fma_f32 v[220:221], v[138:139], v[220:221], v[220:221]
	v_pk_fma_f32 v[136:137], v[244:245], v[218:219], 1.0 op_sel_hi:[1,1,0] neg_lo:[1,0,0] neg_hi:[1,0,0]
	v_pk_fma_f32 v[138:139], v[246:247], v[220:221], 1.0 op_sel_hi:[1,1,0] neg_lo:[1,0,0] neg_hi:[1,0,0]
	v_pk_fma_f32 v[140:141], v[136:137], v[218:219], v[218:219]
	v_pk_fma_f32 v[142:143], v[138:139], v[220:221], v[220:221]
	v_pk_fma_f32 v[136:137], v[244:245], v[140:141], 1.0 op_sel_hi:[1,1,0] neg_lo:[1,0,0] neg_hi:[1,0,0]
	v_pk_fma_f32 v[138:139], v[246:247], v[142:143], 1.0 op_sel_hi:[1,1,0] neg_lo:[1,0,0] neg_hi:[1,0,0]
	v_pk_fma_f32 v[140:141], v[136:137], v[218:219], v[140:141]
	v_pk_fma_f32 v[142:143], v[138:139], v[220:221], v[142:143]
	v_rcp_f32_e32 v241, v240
	v_div_fixup_f32 v244, v140, v244, 1.0
	v_div_fixup_f32 v245, v141, v245, 1.0
	v_div_fixup_f32 v246, v142, v246, 1.0
	v_div_fixup_f32 v247, v143, v247, 1.0
; __device__ __forceinline__ float sigmoidf_(float x) { return 1.0f / (1.0f + __expf(-x)); }
; __device__ __forceinline__ f32x4 cv_bf4(const u32x2 w) { return (f32x4){bflo(w.x), bfhi(w.x), bflo(w.y), bfhi(w.y)}; }
; __device__ __forceinline__ void scan_finish(const ScanPtrs& Q, int J, int ci, unsigned char* buf, int ltid, const LStage& L, int toff) {
;     ...
;         r = r + (rp - r) * *(const f32x4*)mu; k0 = k0 + (kp - k0) * *(const f32x4*)(mu + 512); v = v + (vp - v) * *(const f32x4*)(mu + 1024);
;         const f32x4 kk = k0 * *(const f32x4*)(Q.k_k + gc);
;         const float ss = allsum16((kk[0] * kk[0] + kk[1] * kk[1]) + (kk[2] * kk[2] + kk[3] * kk[3]));
;         const float inv = 1.0f / fmaxf(sqrtf(ss), 1e-12f);
;         const f32x4 kkn = kk * inv;
;         const f32x4 dw = cv_bf4(L.sw) + *(const f32x4*)(Q.decay0 + gc);
;         const f32x4 da = cv_bf4(L.sa) + *(const f32x4*)(Q.a0 + gc);
;         f32x4 dec, ain;
; #pragma unroll
;         for (int j = 0; j < 4; ++j) { dec[j] = __expf(-0.60653066f * sigmoidf_(dw[j])); ain[j] = sigmoidf_(da[j]); }
;         const f32x4 ka = *(const f32x4*)(Q.k_a + gc);
;         const f32x4 kf = k0 * (1.0f + (ain - 1.0f) * ka);
;         const f32x4 rkw = *(const f32x4*)(Q.r_k + gc);
;         const f32x4 pr = r * kf * rkw;
;         const float rk = allsum16((pr[0] + pr[1]) + (pr[2] + pr[3]));
;         unsigned char* tb = buf + tt * SC_TOKB + c * 4;
;         *(f32x4*)(tb) = -kkn; *(f32x4*)(tb + 256) = dec; *(f32x4*)(tb + 512) = kkn * ain; *(f32x4*)(tb + 768) = kf; *(f32x4*)(tb + 1024) = r;
;         if ((c >> 4) == jb.rs) *(f32x4*)(buf + tt * SC_TOKB + 1280 + (c & 15) * 4) = v;
;         if (jb.rs == 0 && c == 0) Q.rk[(size_t)tok * 8 + jb.h] = rk;
	v_fma_f32 v242, -v240, v241, 1.0
	v_fmac_f32_e32 v241, v242, v241
	v_mul_f32_e32 v242, -1.0, v241
	v_fma_f32 v243, -v240, v242, -1.0
	v_fmac_f32_e32 v242, v243, v241
	v_fma_f32 v243, -v240, v242, -1.0
	v_fma_f32 v242, v243, v241, v242
	v_div_fixup_f32 v242, v242, v240, -1.0
	v_pk_mul_f32 v[244:245], v[244:245], v[254:255] op_sel_hi:[1,0]
	v_pk_mul_f32 v[246:247], v[246:247], v[254:255] op_sel_hi:[1,0]
	v_pk_mul_f32 v[244:245], v[244:245], v[226:227] op_sel_hi:[1,0]
	v_pk_mul_f32 v[246:247], v[246:247], v[226:227] op_sel_hi:[1,0]
	v_pk_fma_f32 v[136:137], v[248:249], v[222:223], 1.0 op_sel_hi:[1,1,0] neg_lo:[1,0,0] neg_hi:[1,0,0]
	v_pk_fma_f32 v[138:139], v[250:251], v[224:225], 1.0 op_sel_hi:[1,1,0] neg_lo:[1,0,0] neg_hi:[1,0,0]
	v_pk_fma_f32 v[222:223], v[136:137], v[222:223], v[222:223]
	v_pk_fma_f32 v[224:225], v[138:139], v[224:225], v[224:225]
	v_pk_fma_f32 v[136:137], v[248:249], v[222:223], 1.0 op_sel_hi:[1,1,0] neg_lo:[1,0,0] neg_hi:[1,0,0]
	v_pk_fma_f32 v[138:139], v[250:251], v[224:225], 1.0 op_sel_hi:[1,1,0] neg_lo:[1,0,0] neg_hi:[1,0,0]
	v_pk_fma_f32 v[140:141], v[136:137], v[222:223], v[222:223]
	v_pk_fma_f32 v[142:143], v[138:139], v[224:225], v[224:225]
	v_pk_fma_f32 v[136:137], v[248:249], v[140:141], 1.0 op_sel_hi:[1,1,0] neg_lo:[1,0,0] neg_hi:[1,0,0]
	v_pk_fma_f32 v[138:139], v[250:251], v[142:143], 1.0 op_sel_hi:[1,1,0] neg_lo:[1,0,0] neg_hi:[1,0,0]
	v_pk_fma_f32 v[140:141], v[136:137], v[222:223], v[140:141]
	v_pk_fma_f32 v[142:143], v[138:139], v[224:225], v[142:143]
	v_exp_f32_e32 v244, v244
	v_exp_f32_e32 v245, v245
	v_exp_f32_e32 v246, v246
	v_exp_f32_e32 v247, v247
	v_div_fixup_f32 v248, v140, v248, 1.0
	v_div_fixup_f32 v249, v141, v249, 1.0
	v_div_fixup_f32 v250, v142, v250, 1.0
	v_div_fixup_f32 v251, v143, v251, 1.0
	v_pk_mul_f32 v[218:219], v[236:237], v[242:243] op_sel_hi:[1,0]
	v_pk_mul_f32 v[220:221], v[238:239], v[242:243] op_sel_hi:[1,0]
	v_pk_add_f32 v[136:137], v[248:249], -1.0 op_sel_hi:[1,0]
	v_pk_add_f32 v[138:139], v[250:251], -1.0 op_sel_hi:[1,0]
	v_pk_mul_f32 v[222:223], v[218:219], v[248:249] neg_lo:[1,0] neg_hi:[1,0]
	v_pk_mul_f32 v[224:225], v[220:221], v[250:251] neg_lo:[1,0] neg_hi:[1,0]
	v_pk_fma_f32 v[136:137], v[206:207], v[136:137], 1.0 op_sel_hi:[1,1,0]
	v_pk_fma_f32 v[138:139], v[208:209], v[138:139], 1.0 op_sel_hi:[1,1,0]
	v_lshlrev_b32_e32 v140, 16, v56
	v_and_b32_e32 v141, 0xffff0000, v56
	v_lshlrev_b32_e32 v142, 16, v57
	v_and_b32_e32 v143, 0xffff0000, v57
	v_pk_mul_f32 v[136:137], v[232:233], v[136:137]
	v_pk_mul_f32 v[138:139], v[234:235], v[138:139]
	v_pk_add_f32 v[146:147], v[44:45], v[140:141] neg_lo:[0,1] neg_hi:[0,1]
	v_pk_add_f32 v[148:149], v[46:47], v[142:143] neg_lo:[0,1] neg_hi:[0,1]
	v_pk_fma_f32 v[140:141], v[146:147], v[202:203], v[140:141]
	v_pk_fma_f32 v[142:143], v[148:149], v[204:205], v[142:143]
	v_pk_mul_f32 v[146:147], v[140:141], v[136:137]
	v_pk_mul_f32 v[148:149], v[142:143], v[138:139]
	v_pk_mul_f32 v[146:147], v[210:211], v[146:147]
	v_pk_mul_f32 v[148:149], v[212:213], v[148:149]
	v_add_u32_e32 v26, s6, v105
	v_add_f32_e32 v20, v146, v147
	v_add_f32_e32 v21, v148, v149
	v_add_u32_e32 v27, v26, v100
	v_add_f32_e32 v20, v20, v21
	v_mov_b32_e32 v21, 0
	ds_write_b128 v27, v[218:221]
	v_add_f32_dpp v20, v20, v20 quad_perm:[1,0,3,2] row_mask:0xf bank_mask:0xf bound_ctrl:1
	ds_write_b128 v27, v[244:247] offset:256
	ds_write_b128 v27, v[222:225] offset:512
	v_add_f32_dpp v20, v20, v20 quad_perm:[2,3,0,1] row_mask:0xf bank_mask:0xf bound_ctrl:1
	ds_write_b128 v27, v[136:139] offset:768
	ds_write_b128 v27, v[140:143] offset:1024
	v_add_f32_dpp v20, v20, v20 row_half_mirror row_mask:0xf bank_mask:0xf bound_ctrl:1
	v_cmp_eq_u32_e32 vcc, v101, v121
	s_nop 0
	v_mov_b32_dpp v21, v20 row_mirror row_mask:0xf bank_mask:0xf
	s_and_saveexec_b64 s[16:17], vcc
	s_cbranch_execz .LBB0_497
	v_lshlrev_b32_e32 v32, 16, v68
	v_and_b32_e32 v33, 0xffff0000, v68
	v_lshlrev_b32_e32 v34, 16, v69
	v_and_b32_e32 v35, 0xffff0000, v69
	v_add_u32_e32 v18, v26, v102
	v_sub_f32_e32 v37, v51, v35
	v_sub_f32_e32 v36, v50, v34
	v_sub_f32_e32 v27, v49, v33
	v_sub_f32_e32 v26, v48, v32
	s_waitcnt vmcnt(1)
	v_pk_fma_f32 v[26:27], v[26:27], v[214:215], v[32:33]
	v_pk_fma_f32 v[28:29], v[36:37], v[216:217], v[34:35]
	ds_write_b128 v18, v[26:29] offset:1280

; #define KP(f) ((decltype(Params::f))karg_ptr<(int)offsetof(Params, f)>())
; __device__ void phase_scan(int l, unsigned char* lds) {
;     int tid_ = threadIdx.x; asm volatile("" : "+v"(tid_));
;     const int tid = tid_, wid = tid >> 6, lane = tid & 63, G = gridDim.x;
;     const bool loader = wid >= 4;
;     if (!loader) __builtin_amdgcn_s_setprio(3);
;     ScanPtrs Q;
;     Q.z = KP(z); Q.sw = KP(xb) + (size_t)T_ALL * 512; Q.sa = KP(sc_a); Q.st_shift = KP(state_shift) + (size_t)l * NSB * DSH; Q.mu = KP(mu_shift) + (size_t)l * DSH;
;     Q.k_k = KP(k_k) + (size_t)l * 512; Q.k_a = KP(k_a) + (size_t)l * 512; Q.r_k = KP(r_k) + (size_t)l * 512; Q.decay0 = KP(decay0) + (size_t)l * 512; Q.a0 = KP(a0) + (size_t)l * 512; Q.rk = KP(rk);
;     bf16_t* ybuf = KP(xb);
;     const float* st_wkv = KP(state_wkv); float* out = KP(out);
;     int J = (G % 8 == 0) ? (int)(blockIdx.x % 8) * (G / 8) + (int)(blockIdx.x / 8) : (int)blockIdx.x, ci = 0, it = 0;
;     int Ji = J, cis = 0;
;     int Jg = J, cg_ = 0;
;     LStage L, L2;
;     f32x2 s01 = (f32x2){0.f, 0.f}, s23 = s01;
;     f32x4 s_pref = (f32x4){0.f, 0.f, 0.f, 0.f};
;     if (!loader && J >= 256 && J < NJOBS) { const Job j0 = job_decode(J, 0); s_pref = *(const f32x4*)(st_wkv + (((((size_t)l * NSB + j0.seq) * 8 + j0.h) * 64 + j0.rs * 16 + (wid * 4 + (lane >> 4))) * 64 + (lane & 15) * 4)); }
.LBB0_1542:
	s_or_b64 exec, exec, s[10:11]
	s_mov_b32 s6, s2
	s_mov_b32 s7, s46
	v_mov_b32_e32 v53, v166
	s_waitcnt lgkmcnt(0)
	s_barrier
	s_nop 0
	v_ashrrev_i32_e32 v52, 6, v53
	s_mov_b32 s98, -1
	v_mov_b32_e32 v252, 0xbfb8aa3b
	v_mov_b32_e32 v254, 0xbf1b4598
	v_mov_b32_e32 v226, 0x3fb8aa3b
	v_cmp_lt_i32_e64 s[10:11], 3, v52
	v_cmp_gt_i32_e64 s[12:13], 4, v52
	s_and_saveexec_b64 s[14:15], s[12:13]
	s_setprio 3
	s_or_b64 exec, exec, s[14:15]
	s_load_dwordx2 s[22:23], s[0:1], 0x130
	s_waitcnt lgkmcnt(0)
	s_load_dwordx2 s[16:17], s[0:1], 0x120
	s_waitcnt lgkmcnt(0)
	s_load_dwordx2 s[24:25], s[0:1], 0x140
	s_waitcnt lgkmcnt(0)
	s_load_dwordx2 s[18:19], s[0:1], 16
	s_waitcnt lgkmcnt(0)
	s_load_dwordx2 s[14:15], s[0:1], 56
	s_waitcnt lgkmcnt(0)
	s_load_dwordx2 s[26:27], s[0:1], 0x68
	s_waitcnt lgkmcnt(0)
	s_load_dwordx2 s[28:29], s[0:1], 0x70
	s_waitcnt lgkmcnt(0)
	s_load_dwordx2 s[30:31], s[0:1], 0x78
	s_waitcnt lgkmcnt(0)
	s_load_dwordx2 s[34:35], s[0:1], 64
	s_waitcnt lgkmcnt(0)
	s_load_dwordx2 s[36:37], s[0:1], 0x50
	s_waitcnt lgkmcnt(0)
	s_load_dwordx2 s[38:39], s[0:1], 0x150
	s_waitcnt lgkmcnt(0)
	s_load_dwordx2 s[40:41], s[0:1], 0x120
	s_waitcnt lgkmcnt(0)
	s_load_dwordx2 s[20:21], s[0:1], 32
	s_waitcnt lgkmcnt(0)
	s_load_dwordx2 s[42:43], s[0:1], 0xd8
	s_waitcnt lgkmcnt(0)
	v_readlane_b32 s6, v230, 6
	v_readlane_b32 s7, v230, 7
	s_and_b64 vcc, exec, s[6:7]
	s_mov_b32 s53, s2
	s_cbranch_vccnz .LBB0_1546
	s_and_b32 s6, s2, 7
	s_ashr_i32 s7, s46, 3
	s_mul_i32 s6, s7, s6
	s_lshr_b32 s7, s2, 3
	s_add_i32 s53, s6, s7

; __device__ __forceinline__ float sigmoidf_(float x) { return 1.0f / (1.0f + __expf(-x)); }
; __device__ __forceinline__ f32x4 cv_bf4(const u32x2 w) { return (f32x4){bflo(w.x), bfhi(w.x), bflo(w.y), bfhi(w.y)}; }
; __device__ __forceinline__ void scan_finish(const ScanPtrs& Q, int J, int ci, unsigned char* buf, int ltid, const LStage& L, int toff) {
;     const Job jb = job_decode(J, ci);
;     const int tt = (ltid >> 4) + toff, c = (ltid & 15) * 4;
;     if (tt < jb.nsteps) {
;         const int tok = jb.tok0 + tt; const int tseq = jb.is_s ? tt : ci * SC_CH + tt;
;         const int gc = jb.h * 64 + c;
;         f32x4 r = cv_bf4(L.r), k0 = cv_bf4(L.k), v = cv_bf4(L.v), rp, kp, vp;
;         if (tseq > 0) { rp = cv_bf4(L.rp); kp = cv_bf4(L.kp); vp = cv_bf4(L.vp); }
;         else if (jb.is_s) { rp = L.fr; kp = L.fk; vp = L.fv; }
;         else { rp = (f32x4){0.f, 0.f, 0.f, 0.f}; kp = rp; vp = rp; }
;         const float* mu = Q.mu + gc;
;         r = r + (rp - r) * *(const f32x4*)mu; k0 = k0 + (kp - k0) * *(const f32x4*)(mu + 512); v = v + (vp - v) * *(const f32x4*)(mu + 1024);
;         const f32x4 kk = k0 * *(const f32x4*)(Q.k_k + gc);
;         const float ss = allsum16((kk[0] * kk[0] + kk[1] * kk[1]) + (kk[2] * kk[2] + kk[3] * kk[3]));
;         const float inv = 1.0f / fmaxf(sqrtf(ss), 1e-12f);
;         const f32x4 kkn = kk * inv;
;         const f32x4 dw = cv_bf4(L.sw) + *(const f32x4*)(Q.decay0 + gc);
;         const f32x4 da = cv_bf4(L.sa) + *(const f32x4*)(Q.a0 + gc);
;         f32x4 dec, ain;
; #pragma unroll
;         for (int j = 0; j < 4; ++j) { dec[j] = __expf(-0.60653066f * sigmoidf_(dw[j])); ain[j] = sigmoidf_(da[j]); }
;         const f32x4 ka = *(const f32x4*)(Q.k_a + gc);
;         const f32x4 kf = k0 * (1.0f + (ain - 1.0f) * ka);
;         const f32x4 rkw = *(const f32x4*)(Q.r_k + gc);
;         const f32x4 pr = r * kf * rkw;
;         const float rk = allsum16((pr[0] + pr[1]) + (pr[2] + pr[3]));
.Lprm_ok_1:
	s_waitcnt vmcnt(0)
	v_lshlrev_b32_e32 v232, 16, v70
	v_and_b32_e32 v233, 0xffff0000, v70
	v_lshlrev_b32_e32 v234, 16, v71
	v_and_b32_e32 v235, 0xffff0000, v71
	v_pk_add_f32 v[236:237], v[50:51], v[232:233] neg_lo:[0,1] neg_hi:[0,1]
	v_pk_add_f32 v[238:239], v[52:53], v[234:235] neg_lo:[0,1] neg_hi:[0,1]
	v_pk_fma_f32 v[232:233], v[236:237], v[186:187], v[232:233]
	v_pk_fma_f32 v[234:235], v[238:239], v[188:189], v[234:235]
	v_pk_mul_f32 v[236:237], v[232:233], v[198:199]
	v_pk_mul_f32 v[238:239], v[234:235], v[200:201]
	v_pk_mul_f32 v[240:241], v[236:237], v[236:237]
	v_pk_mul_f32 v[242:243], v[238:239], v[238:239]
	v_add_f32_e32 v240, v240, v241
	v_add_f32_e32 v242, v242, v243
	v_lshlrev_b32_e32 v244, 16, v82
	v_and_b32_e32 v245, 0xffff0000, v82
	v_lshlrev_b32_e32 v246, 16, v83
	v_and_b32_e32 v247, 0xffff0000, v83
	v_add_f32_e32 v240, v240, v242
	v_lshlrev_b32_e32 v248, 16, v84
	v_and_b32_e32 v249, 0xffff0000, v84
	v_lshlrev_b32_e32 v250, 16, v85
	v_and_b32_e32 v251, 0xffff0000, v85
	v_add_f32_dpp v240, v240, v240 quad_perm:[1,0,3,2] row_mask:0xf bank_mask:0xf bound_ctrl:1
	v_pk_add_f32 v[244:245], v[244:245], v[190:191]
	v_pk_add_f32 v[246:247], v[246:247], v[192:193]
	v_add_f32_dpp v240, v240, v240 quad_perm:[2,3,0,1] row_mask:0xf bank_mask:0xf bound_ctrl:1
	v_pk_add_f32 v[248:249], v[248:249], v[194:195]
	v_pk_add_f32 v[250:251], v[250:251], v[196:197]
	v_add_f32_dpp v240, v240, v240 row_half_mirror row_mask:0xf bank_mask:0xf bound_ctrl:1
	v_pk_mul_f32 v[244:245], v[244:245], v[252:253] op_sel_hi:[1,0]
	v_pk_mul_f32 v[246:247], v[246:247], v[252:253] op_sel_hi:[1,0]
	v_add_f32_dpp v240, v240, v240 row_mirror row_mask:0xf bank_mask:0xf bound_ctrl:1
	v_pk_mul_f32 v[248:249], v[248:249], v[252:253] op_sel_hi:[1,0]
	v_pk_mul_f32 v[250:251], v[250:251], v[252:253] op_sel_hi:[1,0]
	v_exp_f32_e32 v244, v244
	v_exp_f32_e32 v245, v245
	v_exp_f32_e32 v246, v246
	v_exp_f32_e32 v247, v247
	v_mul_f32_e32 v241, 0x4f800000, v240
	v_cmp_gt_f32_e32 vcc, s77, v240
	v_exp_f32_e32 v248, v248
	v_exp_f32_e32 v249, v249
	v_cndmask_b32_e32 v240, v240, v241, vcc
	v_sqrt_f32_e32 v241, v240
	v_exp_f32_e32 v250, v250
	v_exp_f32_e32 v251, v251
	v_pk_add_f32 v[244:245], v[244:245], 1.0 op_sel_hi:[1,0]
	v_pk_add_f32 v[246:247], v[246:247], 1.0 op_sel_hi:[1,0]
	v_add_u32_e32 v242, -1, v241
	v_add_u32_e32 v243, 1, v241
	v_fma_f32 v253, -v242, v241, v240
	v_fma_f32 v255, -v243, v241, v240
	v_cmp_ge_f32_e64 s[20:21], 0, v253
	v_pk_add_f32 v[248:249], v[248:249], 1.0 op_sel_hi:[1,0]
	v_pk_add_f32 v[250:251], v[250:251], 1.0 op_sel_hi:[1,0]
	v_cndmask_b32_e64 v241, v241, v242, s[20:21]
	v_cmp_lt_f32_e64 s[20:21], 0, v255
	v_rcp_f32_e32 v218, v244
	v_rcp_f32_e32 v219, v245
	v_cndmask_b32_e64 v241, v241, v243, s[20:21]
	v_rcp_f32_e32 v220, v246
	v_mul_f32_e32 v242, 0x37800000, v241
	v_rcp_f32_e32 v221, v247
	v_cndmask_b32_e32 v241, v241, v242, vcc
	v_cmp_class_f32_e32 vcc, v240, v118
	v_rcp_f32_e32 v222, v248
	v_rcp_f32_e32 v223, v249
	v_cndmask_b32_e32 v240, v241, v240, vcc
	v_rcp_f32_e32 v224, v250
	v_max_f32_e32 v240, 0x2b8cbccc, v240
	v_rcp_f32_e32 v225, v251
	v_pk_fma_f32 v[136:137], v[244:245], v[218:219], 1.0 op_sel_hi:[1,1,0] neg_lo:[1,0,0] neg_hi:[1,0,0]
	v_pk_fma_f32 v[138:139], v[246:247], v[220:221], 1.0 op_sel_hi:[1,1,0] neg_lo:[1,0,0] neg_hi:[1,0,0]
	v_pk_fma_f32 v[218:219], v[136:137], v[218:219], v[218:219]
	v_pk_fma_f32 v[220:221], v[138:139], v[220:221], v[220:221]
	v_pk_fma_f32 v[136:137], v[244:245], v[218:219], 1.0 op_sel_hi:[1,1,0] neg_lo:[1,0,0] neg_hi:[1,0,0]
	v_pk_fma_f32 v[138:139], v[246:247], v[220:221], 1.0 op_sel_hi:[1,1,0] neg_lo:[1,0,0] neg_hi:[1,0,0]
	v_pk_fma_f32 v[140:141], v[136:137], v[218:219], v[218:219]
	v_pk_fma_f32 v[142:143], v[138:139], v[220:221], v[220:221]
	v_pk_fma_f32 v[136:137], v[244:245], v[140:141], 1.0 op_sel_hi:[1,1,0] neg_lo:[1,0,0] neg_hi:[1,0,0]
	v_pk_fma_f32 v[138:139], v[246:247], v[142:143], 1.0 op_sel_hi:[1,1,0] neg_lo:[1,0,0] neg_hi:[1,0,0]
	v_pk_fma_f32 v[140:141], v[136:137], v[218:219], v[140:141]
	v_pk_fma_f32 v[142:143], v[138:139], v[220:221], v[142:143]
	v_rcp_f32_e32 v241, v240
	v_div_fixup_f32 v244, v140, v244, 1.0
	v_div_fixup_f32 v245, v141, v245, 1.0
	v_div_fixup_f32 v246, v142, v246, 1.0
	v_div_fixup_f32 v247, v143, v247, 1.0
; __device__ __forceinline__ float sigmoidf_(float x) { return 1.0f / (1.0f + __expf(-x)); }
; __device__ __forceinline__ f32x4 cv_bf4(const u32x2 w) { return (f32x4){bflo(w.x), bfhi(w.x), bflo(w.y), bfhi(w.y)}; }
; __device__ __forceinline__ void scan_finish(const ScanPtrs& Q, int J, int ci, unsigned char* buf, int ltid, const LStage& L, int toff) {
;     ...
;         r = r + (rp - r) * *(const f32x4*)mu; k0 = k0 + (kp - k0) * *(const f32x4*)(mu + 512); v = v + (vp - v) * *(const f32x4*)(mu + 1024);
;         const f32x4 kk = k0 * *(const f32x4*)(Q.k_k + gc);
;         const float ss = allsum16((kk[0] * kk[0] + kk[1] * kk[1]) + (kk[2] * kk[2] + kk[3] * kk[3]));
;         const float inv = 1.0f / fmaxf(sqrtf(ss), 1e-12f);
;         const f32x4 kkn = kk * inv;
;         const f32x4 dw = cv_bf4(L.sw) + *(const f32x4*)(Q.decay0 + gc);
;         const f32x4 da = cv_bf4(L.sa) + *(const f32x4*)(Q.a0 + gc);
;         f32x4 dec, ain;
; #pragma unroll
;         for (int j = 0; j < 4; ++j) { dec[j] = __expf(-0.60653066f * sigmoidf_(dw[j])); ain[j] = sigmoidf_(da[j]); }
;         const f32x4 ka = *(const f32x4*)(Q.k_a + gc);
;         const f32x4 kf = k0 * (1.0f + (ain - 1.0f) * ka);
;         const f32x4 rkw = *(const f32x4*)(Q.r_k + gc);
;         const f32x4 pr = r * kf * rkw;
;         const float rk = allsum16((pr[0] + pr[1]) + (pr[2] + pr[3]));
;         unsigned char* tb = buf + tt * SC_TOKB + c * 4;
;         *(f32x4*)(tb) = -kkn; *(f32x4*)(tb + 256) = dec; *(f32x4*)(tb + 512) = kkn * ain; *(f32x4*)(tb + 768) = kf; *(f32x4*)(tb + 1024) = r;
;         if ((c >> 4) == jb.rs) *(f32x4*)(buf + tt * SC_TOKB + 1280 + (c & 15) * 4) = v;
;         if (jb.rs == 0 && c == 0) Q.rk[(size_t)tok * 8 + jb.h] = rk;
	v_fma_f32 v242, -v240, v241, 1.0
	v_fmac_f32_e32 v241, v242, v241
	v_mul_f32_e32 v242, -1.0, v241
	v_fma_f32 v243, -v240, v242, -1.0
	v_fmac_f32_e32 v242, v243, v241
	v_fma_f32 v243, -v240, v242, -1.0
	v_fma_f32 v242, v243, v241, v242
	v_div_fixup_f32 v242, v242, v240, -1.0
	v_pk_mul_f32 v[244:245], v[244:245], v[254:255] op_sel_hi:[1,0]
	v_pk_mul_f32 v[246:247], v[246:247], v[254:255] op_sel_hi:[1,0]
	v_pk_mul_f32 v[244:245], v[244:245], v[226:227] op_sel_hi:[1,0]
	v_pk_mul_f32 v[246:247], v[246:247], v[226:227] op_sel_hi:[1,0]
	v_pk_fma_f32 v[136:137], v[248:249], v[222:223], 1.0 op_sel_hi:[1,1,0] neg_lo:[1,0,0] neg_hi:[1,0,0]
	v_pk_fma_f32 v[138:139], v[250:251], v[224:225], 1.0 op_sel_hi:[1,1,0] neg_lo:[1,0,0] neg_hi:[1,0,0]
	v_pk_fma_f32 v[222:223], v[136:137], v[222:223], v[222:223]
	v_pk_fma_f32 v[224:225], v[138:139], v[224:225], v[224:225]
	v_pk_fma_f32 v[136:137], v[248:249], v[222:223], 1.0 op_sel_hi:[1,1,0] neg_lo:[1,0,0] neg_hi:[1,0,0]
	v_pk_fma_f32 v[138:139], v[250:251], v[224:225], 1.0 op_sel_hi:[1,1,0] neg_lo:[1,0,0] neg_hi:[1,0,0]
	v_pk_fma_f32 v[140:141], v[136:137], v[222:223], v[222:223]
	v_pk_fma_f32 v[142:143], v[138:139], v[224:225], v[224:225]
	v_pk_fma_f32 v[136:137], v[248:249], v[140:141], 1.0 op_sel_hi:[1,1,0] neg_lo:[1,0,0] neg_hi:[1,0,0]
	v_pk_fma_f32 v[138:139], v[250:251], v[142:143], 1.0 op_sel_hi:[1,1,0] neg_lo:[1,0,0] neg_hi:[1,0,0]
	v_pk_fma_f32 v[140:141], v[136:137], v[222:223], v[140:141]
	v_pk_fma_f32 v[142:143], v[138:139], v[224:225], v[142:143]
	v_exp_f32_e32 v244, v244
	v_exp_f32_e32 v245, v245
	v_exp_f32_e32 v246, v246
	v_exp_f32_e32 v247, v247
	v_div_fixup_f32 v248, v140, v248, 1.0
	v_div_fixup_f32 v249, v141, v249, 1.0
	v_div_fixup_f32 v250, v142, v250, 1.0
	v_div_fixup_f32 v251, v143, v251, 1.0
	v_pk_mul_f32 v[218:219], v[236:237], v[242:243] op_sel_hi:[1,0]
	v_pk_mul_f32 v[220:221], v[238:239], v[242:243] op_sel_hi:[1,0]
	v_pk_add_f32 v[136:137], v[248:249], -1.0 op_sel_hi:[1,0]
	v_pk_add_f32 v[138:139], v[250:251], -1.0 op_sel_hi:[1,0]
	v_pk_mul_f32 v[222:223], v[218:219], v[248:249] neg_lo:[1,0] neg_hi:[1,0]
	v_pk_mul_f32 v[224:225], v[220:221], v[250:251] neg_lo:[1,0] neg_hi:[1,0]
	v_pk_fma_f32 v[136:137], v[206:207], v[136:137], 1.0 op_sel_hi:[1,1,0]
	v_pk_fma_f32 v[138:139], v[208:209], v[138:139], 1.0 op_sel_hi:[1,1,0]
	v_lshlrev_b32_e32 v140, 16, v62
	v_and_b32_e32 v141, 0xffff0000, v62
	v_lshlrev_b32_e32 v142, 16, v63
	v_and_b32_e32 v143, 0xffff0000, v63
	v_pk_mul_f32 v[136:137], v[232:233], v[136:137]
	v_pk_mul_f32 v[138:139], v[234:235], v[138:139]
	v_pk_add_f32 v[146:147], v[46:47], v[140:141] neg_lo:[0,1] neg_hi:[0,1]
	v_pk_add_f32 v[148:149], v[48:49], v[142:143] neg_lo:[0,1] neg_hi:[0,1]
	v_pk_fma_f32 v[140:141], v[146:147], v[202:203], v[140:141]
	v_pk_fma_f32 v[142:143], v[148:149], v[204:205], v[142:143]
	v_pk_mul_f32 v[146:147], v[140:141], v[136:137]
	v_pk_mul_f32 v[148:149], v[142:143], v[138:139]
	v_pk_mul_f32 v[146:147], v[210:211], v[146:147]
	v_pk_mul_f32 v[148:149], v[212:213], v[148:149]
	v_add_u32_e32 v30, s6, v99
	v_add_f32_e32 v20, v146, v147
	v_add_f32_e32 v21, v148, v149
	v_add_u32_e32 v31, v30, v100
	v_add_f32_e32 v20, v20, v21
	v_mov_b32_e32 v21, 0
	ds_write_b128 v31, v[218:221]
	v_add_f32_dpp v20, v20, v20 quad_perm:[1,0,3,2] row_mask:0xf bank_mask:0xf bound_ctrl:1
	ds_write_b128 v31, v[244:247] offset:256
	ds_write_b128 v31, v[222:225] offset:512
	v_add_f32_dpp v20, v20, v20 quad_perm:[2,3,0,1] row_mask:0xf bank_mask:0xf bound_ctrl:1
	ds_write_b128 v31, v[136:139] offset:768
	ds_write_b128 v31, v[140:143] offset:1024
	v_add_f32_dpp v20, v20, v20 row_half_mirror row_mask:0xf bank_mask:0xf bound_ctrl:1
	v_cmp_eq_u32_e32 vcc, v101, v121
	s_nop 0
	v_mov_b32_dpp v21, v20 row_mirror row_mask:0xf bank_mask:0xf
	s_and_saveexec_b64 s[16:17], vcc
	s_cbranch_execz .LBB0_1631
	v_lshlrev_b32_e32 v36, 16, v72
	v_and_b32_e32 v37, 0xffff0000, v72
	v_lshlrev_b32_e32 v38, 16, v73
	v_and_b32_e32 v39, 0xffff0000, v73
	v_sub_f32_e32 v29, v29, v39
	v_sub_f32_e32 v28, v28, v38
	v_sub_f32_e32 v27, v27, v37
	v_sub_f32_e32 v26, v26, v36
	v_add_u32_e32 v18, v30, v102
	s_waitcnt vmcnt(0)
	v_pk_fma_f32 v[26:27], v[26:27], v[214:215], v[36:37]
	v_pk_fma_f32 v[28:29], v[28:29], v[216:217], v[38:39]
	ds_write_b128 v18, v[26:29] offset:1280

; __device__ __forceinline__ float sigmoidf_(float x) { return 1.0f / (1.0f + __expf(-x)); }
; __device__ __forceinline__ f32x4 cv_bf4(const u32x2 w) { return (f32x4){bflo(w.x), bfhi(w.x), bflo(w.y), bfhi(w.y)}; }
; __device__ __forceinline__ void scan_finish(const ScanPtrs& Q, int J, int ci, unsigned char* buf, int ltid, const LStage& L, int toff) {
;     ...
;         f32x4 r = cv_bf4(L.r), k0 = cv_bf4(L.k), v = cv_bf4(L.v), rp, kp, vp;
;         if (tseq > 0) { rp = cv_bf4(L.rp); kp = cv_bf4(L.kp); vp = cv_bf4(L.vp); }
;         else if (jb.is_s) { rp = L.fr; kp = L.fk; vp = L.fv; }
;         else { rp = (f32x4){0.f, 0.f, 0.f, 0.f}; kp = rp; vp = rp; }
;         const float* mu = Q.mu + gc;
;         r = r + (rp - r) * *(const f32x4*)mu; k0 = k0 + (kp - k0) * *(const f32x4*)(mu + 512); v = v + (vp - v) * *(const f32x4*)(mu + 1024);
;         const f32x4 kk = k0 * *(const f32x4*)(Q.k_k + gc);
;         const float ss = allsum16((kk[0] * kk[0] + kk[1] * kk[1]) + (kk[2] * kk[2] + kk[3] * kk[3]));
;         const float inv = 1.0f / fmaxf(sqrtf(ss), 1e-12f);
;         const f32x4 kkn = kk * inv;
;         const f32x4 dw = cv_bf4(L.sw) + *(const f32x4*)(Q.decay0 + gc);
;         const f32x4 da = cv_bf4(L.sa) + *(const f32x4*)(Q.a0 + gc);
;         f32x4 dec, ain;
; #pragma unroll
;         for (int j = 0; j < 4; ++j) { dec[j] = __expf(-0.60653066f * sigmoidf_(dw[j])); ain[j] = sigmoidf_(da[j]); }
;         const f32x4 ka = *(const f32x4*)(Q.k_a + gc);
;         const f32x4 kf = k0 * (1.0f + (ain - 1.0f) * ka);
.LBB0_1636:
	s_or_b64 exec, exec, s[14:15]
	v_lshl_or_b32 v18, v91, 8, v100
	s_waitcnt vmcnt(1)
	v_lshlrev_b32_e32 v232, 16, v60
	v_and_b32_e32 v233, 0xffff0000, v60
	v_lshlrev_b32_e32 v234, 16, v61
	v_and_b32_e32 v235, 0xffff0000, v61
	v_sub_f32_e32 v236, v52, v232
	v_sub_f32_e32 v237, v92, v233
	v_sub_f32_e32 v238, v53, v234
	v_sub_f32_e32 v239, v93, v235
	v_pk_fma_f32 v[232:233], v[236:237], v[186:187], v[232:233]
	v_pk_fma_f32 v[234:235], v[238:239], v[188:189], v[234:235]
	v_pk_mul_f32 v[236:237], v[232:233], v[198:199]
	v_pk_mul_f32 v[238:239], v[234:235], v[200:201]
	v_pk_mul_f32 v[240:241], v[236:237], v[236:237]
	v_pk_mul_f32 v[242:243], v[238:239], v[238:239]
	v_add_f32_e32 v240, v240, v241
	v_add_f32_e32 v242, v242, v243
	v_lshlrev_b32_e32 v244, 16, v78
	v_and_b32_e32 v245, 0xffff0000, v78
	v_lshlrev_b32_e32 v246, 16, v79
	v_and_b32_e32 v247, 0xffff0000, v79
	v_add_f32_e32 v240, v240, v242
	v_lshlrev_b32_e32 v248, 16, v80
	v_and_b32_e32 v249, 0xffff0000, v80
	v_lshlrev_b32_e32 v250, 16, v81
	v_and_b32_e32 v251, 0xffff0000, v81
	v_add_f32_dpp v240, v240, v240 quad_perm:[1,0,3,2] row_mask:0xf bank_mask:0xf bound_ctrl:1
	v_pk_add_f32 v[244:245], v[244:245], v[190:191]
	v_pk_add_f32 v[246:247], v[246:247], v[192:193]
	v_add_f32_dpp v240, v240, v240 quad_perm:[2,3,0,1] row_mask:0xf bank_mask:0xf bound_ctrl:1
	v_pk_add_f32 v[248:249], v[248:249], v[194:195]
	v_pk_add_f32 v[250:251], v[250:251], v[196:197]
	v_add_f32_dpp v240, v240, v240 row_half_mirror row_mask:0xf bank_mask:0xf bound_ctrl:1
	v_pk_mul_f32 v[244:245], v[244:245], v[252:253] op_sel_hi:[1,0]
	v_pk_mul_f32 v[246:247], v[246:247], v[252:253] op_sel_hi:[1,0]
	v_add_f32_dpp v240, v240, v240 row_mirror row_mask:0xf bank_mask:0xf bound_ctrl:1
	v_pk_mul_f32 v[248:249], v[248:249], v[252:253] op_sel_hi:[1,0]
	v_pk_mul_f32 v[250:251], v[250:251], v[252:253] op_sel_hi:[1,0]
	v_exp_f32_e32 v244, v244
	v_exp_f32_e32 v245, v245
	v_exp_f32_e32 v246, v246
	v_exp_f32_e32 v247, v247
	v_mul_f32_e32 v241, 0x4f800000, v240
	v_cmp_gt_f32_e32 vcc, s77, v240
	v_exp_f32_e32 v248, v248
	v_exp_f32_e32 v249, v249
	v_cndmask_b32_e32 v240, v240, v241, vcc
	v_sqrt_f32_e32 v241, v240
	v_exp_f32_e32 v250, v250
	v_exp_f32_e32 v251, v251
	v_pk_add_f32 v[244:245], v[244:245], 1.0 op_sel_hi:[1,0]
	v_pk_add_f32 v[246:247], v[246:247], 1.0 op_sel_hi:[1,0]
	v_add_u32_e32 v242, -1, v241
	v_add_u32_e32 v243, 1, v241
	v_fma_f32 v253, -v242, v241, v240
	v_fma_f32 v255, -v243, v241, v240
	v_cmp_ge_f32_e64 s[18:19], 0, v253
	v_pk_add_f32 v[248:249], v[248:249], 1.0 op_sel_hi:[1,0]
	v_pk_add_f32 v[250:251], v[250:251], 1.0 op_sel_hi:[1,0]
	v_cndmask_b32_e64 v241, v241, v242, s[18:19]
	v_cmp_lt_f32_e64 s[18:19], 0, v255
	v_rcp_f32_e32 v218, v244
	v_rcp_f32_e32 v219, v245
	v_cndmask_b32_e64 v241, v241, v243, s[18:19]
	v_rcp_f32_e32 v220, v246
	v_mul_f32_e32 v242, 0x37800000, v241
	v_rcp_f32_e32 v221, v247
	v_cndmask_b32_e32 v241, v241, v242, vcc
	v_cmp_class_f32_e32 vcc, v240, v118
	v_rcp_f32_e32 v222, v248
	v_rcp_f32_e32 v223, v249
	v_cndmask_b32_e32 v240, v241, v240, vcc
	v_rcp_f32_e32 v224, v250
	v_max_f32_e32 v240, 0x2b8cbccc, v240
	v_rcp_f32_e32 v225, v251
	v_pk_fma_f32 v[136:137], v[244:245], v[218:219], 1.0 op_sel_hi:[1,1,0] neg_lo:[1,0,0] neg_hi:[1,0,0]
	v_pk_fma_f32 v[138:139], v[246:247], v[220:221], 1.0 op_sel_hi:[1,1,0] neg_lo:[1,0,0] neg_hi:[1,0,0]
	v_pk_fma_f32 v[218:219], v[136:137], v[218:219], v[218:219]
	v_pk_fma_f32 v[220:221], v[138:139], v[220:221], v[220:221]
	v_pk_fma_f32 v[136:137], v[244:245], v[218:219], 1.0 op_sel_hi:[1,1,0] neg_lo:[1,0,0] neg_hi:[1,0,0]
	v_pk_fma_f32 v[138:139], v[246:247], v[220:221], 1.0 op_sel_hi:[1,1,0] neg_lo:[1,0,0] neg_hi:[1,0,0]
	v_pk_fma_f32 v[140:141], v[136:137], v[218:219], v[218:219]
	v_pk_fma_f32 v[142:143], v[138:139], v[220:221], v[220:221]
	v_pk_fma_f32 v[136:137], v[244:245], v[140:141], 1.0 op_sel_hi:[1,1,0] neg_lo:[1,0,0] neg_hi:[1,0,0]
	v_pk_fma_f32 v[138:139], v[246:247], v[142:143], 1.0 op_sel_hi:[1,1,0] neg_lo:[1,0,0] neg_hi:[1,0,0]
	v_pk_fma_f32 v[140:141], v[136:137], v[218:219], v[140:141]
	v_pk_fma_f32 v[142:143], v[138:139], v[220:221], v[142:143]
	v_rcp_f32_e32 v241, v240
	v_div_fixup_f32 v244, v140, v244, 1.0
	v_div_fixup_f32 v245, v141, v245, 1.0
	v_div_fixup_f32 v246, v142, v246, 1.0
	v_div_fixup_f32 v247, v143, v247, 1.0
; __device__ __forceinline__ float sigmoidf_(float x) { return 1.0f / (1.0f + __expf(-x)); }
; __device__ __forceinline__ f32x4 cv_bf4(const u32x2 w) { return (f32x4){bflo(w.x), bfhi(w.x), bflo(w.y), bfhi(w.y)}; }
; __device__ __forceinline__ void scan_finish(const ScanPtrs& Q, int J, int ci, unsigned char* buf, int ltid, const LStage& L, int toff) {
;     ...
;         const float inv = 1.0f / fmaxf(sqrtf(ss), 1e-12f);
;         const f32x4 kkn = kk * inv;
;         const f32x4 dw = cv_bf4(L.sw) + *(const f32x4*)(Q.decay0 + gc);
;         const f32x4 da = cv_bf4(L.sa) + *(const f32x4*)(Q.a0 + gc);
;         f32x4 dec, ain;
; #pragma unroll
;         for (int j = 0; j < 4; ++j) { dec[j] = __expf(-0.60653066f * sigmoidf_(dw[j])); ain[j] = sigmoidf_(da[j]); }
;         const f32x4 ka = *(const f32x4*)(Q.k_a + gc);
;         const f32x4 kf = k0 * (1.0f + (ain - 1.0f) * ka);
;         const f32x4 rkw = *(const f32x4*)(Q.r_k + gc);
;         const f32x4 pr = r * kf * rkw;
;         const float rk = allsum16((pr[0] + pr[1]) + (pr[2] + pr[3]));
;         unsigned char* tb = buf + tt * SC_TOKB + c * 4;
;         *(f32x4*)(tb) = -kkn; *(f32x4*)(tb + 256) = dec; *(f32x4*)(tb + 512) = kkn * ain; *(f32x4*)(tb + 768) = kf; *(f32x4*)(tb + 1024) = r;
;         if ((c >> 4) == jb.rs) *(f32x4*)(buf + tt * SC_TOKB + 1280 + (c & 15) * 4) = v;
;         if (jb.rs == 0 && c == 0) Q.rk[(size_t)tok * 8 + jb.h] = rk;
;     }
	v_fma_f32 v242, -v240, v241, 1.0
	v_fmac_f32_e32 v241, v242, v241
	v_mul_f32_e32 v242, -1.0, v241
	v_fma_f32 v243, -v240, v242, -1.0
	v_fmac_f32_e32 v242, v243, v241
	v_fma_f32 v243, -v240, v242, -1.0
	v_fma_f32 v242, v243, v241, v242
	v_div_fixup_f32 v242, v242, v240, -1.0
	v_pk_mul_f32 v[244:245], v[244:245], v[254:255] op_sel_hi:[1,0]
	v_pk_mul_f32 v[246:247], v[246:247], v[254:255] op_sel_hi:[1,0]
	v_pk_mul_f32 v[244:245], v[244:245], v[226:227] op_sel_hi:[1,0]
	v_pk_mul_f32 v[246:247], v[246:247], v[226:227] op_sel_hi:[1,0]
	v_pk_fma_f32 v[136:137], v[248:249], v[222:223], 1.0 op_sel_hi:[1,1,0] neg_lo:[1,0,0] neg_hi:[1,0,0]
	v_pk_fma_f32 v[138:139], v[250:251], v[224:225], 1.0 op_sel_hi:[1,1,0] neg_lo:[1,0,0] neg_hi:[1,0,0]
	v_pk_fma_f32 v[222:223], v[136:137], v[222:223], v[222:223]
	v_pk_fma_f32 v[224:225], v[138:139], v[224:225], v[224:225]
	v_pk_fma_f32 v[136:137], v[248:249], v[222:223], 1.0 op_sel_hi:[1,1,0] neg_lo:[1,0,0] neg_hi:[1,0,0]
	v_pk_fma_f32 v[138:139], v[250:251], v[224:225], 1.0 op_sel_hi:[1,1,0] neg_lo:[1,0,0] neg_hi:[1,0,0]
	v_pk_fma_f32 v[140:141], v[136:137], v[222:223], v[222:223]
	v_pk_fma_f32 v[142:143], v[138:139], v[224:225], v[224:225]
	v_pk_fma_f32 v[136:137], v[248:249], v[140:141], 1.0 op_sel_hi:[1,1,0] neg_lo:[1,0,0] neg_hi:[1,0,0]
	v_pk_fma_f32 v[138:139], v[250:251], v[142:143], 1.0 op_sel_hi:[1,1,0] neg_lo:[1,0,0] neg_hi:[1,0,0]
	v_pk_fma_f32 v[140:141], v[136:137], v[222:223], v[140:141]
	v_pk_fma_f32 v[142:143], v[138:139], v[224:225], v[142:143]
	v_exp_f32_e32 v244, v244
	v_exp_f32_e32 v245, v245
	v_exp_f32_e32 v246, v246
	v_exp_f32_e32 v247, v247
	v_div_fixup_f32 v248, v140, v248, 1.0
	v_div_fixup_f32 v249, v141, v249, 1.0
	v_div_fixup_f32 v250, v142, v250, 1.0
	v_div_fixup_f32 v251, v143, v251, 1.0
	v_pk_mul_f32 v[218:219], v[236:237], v[242:243] op_sel_hi:[1,0]
	v_pk_mul_f32 v[220:221], v[238:239], v[242:243] op_sel_hi:[1,0]
	v_pk_add_f32 v[136:137], v[248:249], -1.0 op_sel_hi:[1,0]
	v_pk_add_f32 v[138:139], v[250:251], -1.0 op_sel_hi:[1,0]
	v_pk_mul_f32 v[222:223], v[218:219], v[248:249] neg_lo:[1,0] neg_hi:[1,0]
	v_pk_mul_f32 v[224:225], v[220:221], v[250:251] neg_lo:[1,0] neg_hi:[1,0]
	v_pk_fma_f32 v[136:137], v[206:207], v[136:137], 1.0 op_sel_hi:[1,1,0]
	v_pk_fma_f32 v[138:139], v[208:209], v[138:139], 1.0 op_sel_hi:[1,1,0]
	v_lshlrev_b32_e32 v140, 16, v56
	v_and_b32_e32 v141, 0xffff0000, v56
	v_lshlrev_b32_e32 v142, 16, v57
	v_and_b32_e32 v143, 0xffff0000, v57
	v_pk_mul_f32 v[136:137], v[232:233], v[136:137]
	v_pk_mul_f32 v[138:139], v[234:235], v[138:139]
	v_pk_add_f32 v[146:147], v[44:45], v[140:141] neg_lo:[0,1] neg_hi:[0,1]
	v_pk_add_f32 v[148:149], v[46:47], v[142:143] neg_lo:[0,1] neg_hi:[0,1]
	v_pk_fma_f32 v[140:141], v[146:147], v[202:203], v[140:141]
	v_pk_fma_f32 v[142:143], v[148:149], v[204:205], v[142:143]
	v_pk_mul_f32 v[146:147], v[140:141], v[136:137]
	v_pk_mul_f32 v[148:149], v[142:143], v[138:139]
	v_pk_mul_f32 v[146:147], v[210:211], v[146:147]
	v_pk_mul_f32 v[148:149], v[212:213], v[148:149]
	v_add_u32_e32 v26, s6, v105
	v_add_f32_e32 v20, v146, v147
	v_add_f32_e32 v21, v148, v149
	v_add_u32_e32 v27, v26, v100
	v_add_f32_e32 v20, v20, v21
	v_mov_b32_e32 v21, 0
	ds_write_b128 v27, v[218:221]
	v_add_f32_dpp v20, v20, v20 quad_perm:[1,0,3,2] row_mask:0xf bank_mask:0xf bound_ctrl:1
	ds_write_b128 v27, v[244:247] offset:256
	ds_write_b128 v27, v[222:225] offset:512
	v_add_f32_dpp v20, v20, v20 quad_perm:[2,3,0,1] row_mask:0xf bank_mask:0xf bound_ctrl:1
	ds_write_b128 v27, v[136:139] offset:768
	ds_write_b128 v27, v[140:143] offset:1024
	v_add_f32_dpp v20, v20, v20 row_half_mirror row_mask:0xf bank_mask:0xf bound_ctrl:1
	v_cmp_eq_u32_e32 vcc, v101, v121
	s_nop 0
	v_mov_b32_dpp v21, v20 row_mirror row_mask:0xf bank_mask:0xf
	s_and_saveexec_b64 s[14:15], vcc
	s_cbranch_execz .LBB0_1638
	v_lshlrev_b32_e32 v32, 16, v68
	v_and_b32_e32 v33, 0xffff0000, v68
	v_lshlrev_b32_e32 v34, 16, v69
	v_and_b32_e32 v35, 0xffff0000, v69
	v_add_u32_e32 v18, v26, v102
	v_sub_f32_e32 v37, v51, v35
	v_sub_f32_e32 v36, v50, v34
	v_sub_f32_e32 v27, v49, v33
	v_sub_f32_e32 v26, v48, v32
	s_waitcnt vmcnt(1)
	v_pk_fma_f32 v[26:27], v[26:27], v[214:215], v[32:33]
	v_pk_fma_f32 v[28:29], v[36:37], v[216:217], v[34:35]
	ds_write_b128 v18, v[26:29] offset:1280
